# attention steady loop: back-edge bookkeeping rotated in front of the closing barriers, first QK MFMA leads each step
# speedup vs baseline: 1.0059x; 1.0003x over previous
.LBB0_871:
	s_mov_b32 s54, s72
	s_mov_b32 s18, s19
	s_mov_b32 s16, s59
	v_mfma_f32_32x32x16_bf16 v[80:95], v[172:175], v[124:127], 0
	v_lshl_add_u64 v[250:251], v[214:215], 0, s[50:51]
	s_add_i32 s98, s59, s68
	s_mov_b32 s99, m0
	s_mov_b32 m0, s98
	v_lshl_add_u64 v[252:253], v[212:213], 0, s[50:51]
	s_nop 0
	global_load_lds_dwordx4 v[250:251], off
	s_add_i32 s98, s72, s69
	s_mov_b32 m0, s98
	s_nop 0
	global_load_lds_dwordx4 v[252:253], off
	s_mov_b32 m0, s99
	v_add_u32_e32 v34, s17, v235
	ds_read_b64_tr_b16 v[190:191], v34 offset:24576
	ds_read_b64_tr_b16 v[192:193], v34 offset:25088
	v_add_f32_e32 v35, v64, v65
	v_add_f32_e32 v35, v66, v35
	v_add_f32_e32 v35, v67, v35
	v_add_f32_e32 v35, v68, v35
	v_add_f32_e32 v35, v69, v35
	s_waitcnt lgkmcnt(9)
	v_cvt_pk_bf16_f32 v174, v64, v65
	v_cvt_pk_bf16_f32 v175, v66, v67
	ds_read_b64_tr_b16 v[194:195], v34 offset:28672
	ds_read_b64_tr_b16 v[196:197], v34 offset:29184
	v_add_f32_e32 v35, v70, v35
	v_add_f32_e32 v35, v71, v35
	v_add_f32_e32 v35, v72, v35
	v_add_f32_e32 v35, v73, v35
	v_cvt_pk_bf16_f32 v176, v68, v69
	v_cvt_pk_bf16_f32 v177, v70, v71
	s_waitcnt lgkmcnt(10)
	v_mfma_f32_32x32x16_bf16 v[96:111], v[164:167], v[124:127], 0
	ds_read_b64_tr_b16 v[164:165], v34 offset:25600
	ds_read_b64_tr_b16 v[166:167], v34 offset:26112
	v_add_f32_e32 v35, v74, v35
	v_add_f32_e32 v35, v75, v35
	v_add_f32_e32 v35, v76, v35
	v_add_f32_e32 v35, v77, v35
	v_cvt_pk_bf16_f32 v178, v72, v73
	v_cvt_pk_bf16_f32 v179, v74, v75
	s_waitcnt lgkmcnt(11)
	v_mfma_f32_32x32x16_bf16 v[80:95], v[168:171], v[120:123], v[80:95]
	ds_read_b64_tr_b16 v[168:169], v34 offset:29696
	ds_read_b64_tr_b16 v[170:171], v34 offset:30208
	v_add_f32_e32 v35, v78, v35
	v_add_f32_e32 v35, v79, v35
	v_add_f32_e32 v35, v48, v35
	v_add_f32_e32 v35, v49, v35
	v_cvt_pk_bf16_f32 v180, v76, v77
	v_cvt_pk_bf16_f32 v181, v78, v79
	s_waitcnt lgkmcnt(12)
	v_mfma_f32_32x32x16_bf16 v[96:111], v[160:163], v[120:123], v[96:111]
	ds_read_b64_tr_b16 v[160:161], v34 offset:26624
	ds_read_b64_tr_b16 v[162:163], v34 offset:27136
	v_add_f32_e32 v35, v50, v35
	v_add_f32_e32 v35, v51, v35
	v_add_f32_e32 v35, v52, v35
	v_add_f32_e32 v35, v53, v35
	v_cvt_pk_bf16_f32 v182, v48, v49
	v_cvt_pk_bf16_f32 v183, v50, v51
	s_waitcnt lgkmcnt(13)
	v_mfma_f32_32x32x16_bf16 v[80:95], v[156:159], v[116:119], v[80:95]
	ds_read_b64_tr_b16 v[156:157], v34 offset:30720
	ds_read_b64_tr_b16 v[158:159], v34 offset:31232
	v_add_f32_e32 v35, v54, v35
	v_add_f32_e32 v35, v55, v35
	v_add_f32_e32 v35, v56, v35
	v_add_f32_e32 v35, v57, v35
	v_cvt_pk_bf16_f32 v184, v52, v53
	v_cvt_pk_bf16_f32 v185, v54, v55
	s_waitcnt lgkmcnt(14)
	v_mfma_f32_32x32x16_bf16 v[96:111], v[152:155], v[116:119], v[96:111]
	ds_read_b64_tr_b16 v[152:153], v34 offset:27648
	ds_read_b64_tr_b16 v[154:155], v34 offset:28160
	v_add_f32_e32 v35, v58, v35
	v_add_f32_e32 v35, v59, v35
	v_add_f32_e32 v35, v60, v35
	v_add_f32_e32 v35, v61, v35
	v_cvt_pk_bf16_f32 v186, v56, v57
	v_cvt_pk_bf16_f32 v187, v58, v59
	s_waitcnt lgkmcnt(14)
	v_mfma_f32_32x32x16_bf16 v[80:95], v[148:151], v[112:115], v[80:95]
	ds_read_b64_tr_b16 v[148:149], v34 offset:31744
	ds_read_b64_tr_b16 v[150:151], v34 offset:32256
	v_add_f32_e32 v34, v62, v35
	v_add_f32_e32 v34, v63, v34
	v_add_f32_e32 v172, 0, v34
	v_cvt_pk_bf16_f32 v188, v60, v61
	v_cvt_pk_bf16_f32 v189, v62, v63
	v_mfma_f32_32x32x16_bf16 v[96:111], v[144:147], v[112:115], v[96:111]
	ds_read_b128 v[34:37], v33 offset:128
	ds_read_b128 v[38:41], v33
	ds_read_b128 v[42:45], v33 offset:32
	s_waitcnt lgkmcnt(2)
	v_sub_f32_e32 v34, v206, v34
	s_nop 2
	v_add_f32_e32 v70, v96, v34
	s_waitcnt lgkmcnt(1)
	v_sub_f32_e32 v34, v206, v39
	v_add_f32_e32 v51, v81, v34
	v_sub_f32_e32 v34, v206, v35
	v_add_f32_e32 v71, v97, v34
	v_sub_f32_e32 v34, v206, v40
	v_add_f32_e32 v52, v82, v34
	v_sub_f32_e32 v34, v206, v36
	v_add_f32_e32 v72, v98, v34
	v_sub_f32_e32 v34, v206, v41
	v_add_f32_e32 v53, v83, v34
	v_sub_f32_e32 v34, v206, v37
	v_add_f32_e32 v73, v99, v34
	ds_read_b128 v[34:37], v33 offset:160
	v_sub_f32_e32 v38, v206, v38
	v_add_f32_e32 v50, v80, v38
	s_waitcnt lgkmcnt(1)
	v_pk_add_f32 v[38:39], v[206:207], v[42:43] neg_lo:[0,1] neg_hi:[0,1]
	s_waitcnt lgkmcnt(0)
	v_pk_add_f32 v[34:35], v[206:207], v[34:35] neg_lo:[0,1] neg_hi:[0,1]
	v_pk_add_f32 v[54:55], v[84:85], v[38:39]
	v_pk_add_f32 v[38:39], v[100:101], v[34:35]
	v_pk_add_f32 v[34:35], v[206:207], v[44:45] neg_lo:[0,1] neg_hi:[0,1]
	s_nop 0
	v_pk_add_f32 v[56:57], v[86:87], v[34:35]
	v_pk_add_f32 v[34:35], v[206:207], v[36:37] neg_lo:[0,1] neg_hi:[0,1]
	s_nop 0
	v_pk_add_f32 v[40:41], v[102:103], v[34:35]
	ds_read_b128 v[34:37], v33 offset:64
	ds_read_b128 v[42:45], v33 offset:192
	s_waitcnt lgkmcnt(1)
	v_pk_add_f32 v[34:35], v[206:207], v[34:35] neg_lo:[0,1] neg_hi:[0,1]
	s_nop 0
	v_pk_add_f32 v[58:59], v[88:89], v[34:35]
	s_waitcnt lgkmcnt(0)
	v_pk_add_f32 v[34:35], v[206:207], v[42:43] neg_lo:[0,1] neg_hi:[0,1]
	s_nop 0
	v_pk_add_f32 v[42:43], v[104:105], v[34:35]
	v_pk_add_f32 v[34:35], v[206:207], v[36:37] neg_lo:[0,1] neg_hi:[0,1]
	s_nop 0
	v_pk_add_f32 v[60:61], v[90:91], v[34:35]
	v_pk_add_f32 v[34:35], v[206:207], v[44:45] neg_lo:[0,1] neg_hi:[0,1]
	s_nop 0
	v_pk_add_f32 v[44:45], v[106:107], v[34:35]
	ds_read_b128 v[34:37], v33 offset:96
	ds_read_b128 v[46:49], v33 offset:224
	s_waitcnt lgkmcnt(1)
	v_pk_add_f32 v[34:35], v[206:207], v[34:35] neg_lo:[0,1] neg_hi:[0,1]
	s_nop 0
	v_pk_add_f32 v[62:63], v[92:93], v[34:35]
	s_waitcnt lgkmcnt(0)
	v_pk_add_f32 v[34:35], v[206:207], v[46:47] neg_lo:[0,1] neg_hi:[0,1]
	s_nop 0
	v_pk_add_f32 v[46:47], v[108:109], v[34:35]
	v_pk_add_f32 v[34:35], v[206:207], v[36:37] neg_lo:[0,1] neg_hi:[0,1]
	s_nop 0
	v_pk_add_f32 v[64:65], v[94:95], v[34:35]
	v_pk_add_f32 v[34:35], v[206:207], v[48:49] neg_lo:[0,1] neg_hi:[0,1]
	s_nop 0
	v_pk_add_f32 v[48:49], v[110:111], v[34:35]
	v_exp_f32_e32 v50, v50
	v_exp_f32_e32 v51, v51
	v_exp_f32_e32 v52, v52
	v_exp_f32_e32 v53, v53
	s_nop 0
	v_exp_f32_e32 v54, v54
	v_exp_f32_e32 v55, v55
	v_exp_f32_e32 v56, v56
	v_exp_f32_e32 v57, v57
	v_add_u32_e32 v74, s54, v233
	ds_read_b128 v[66:69], v74
	ds_read_b128 v[82:85], v74 offset:512
	v_exp_f32_e32 v58, v58
	v_exp_f32_e32 v59, v59
	v_exp_f32_e32 v60, v60
	v_exp_f32_e32 v61, v61
	ds_read_b128 v[102:105], v74 offset:2048
	ds_read_b128 v[132:135], v74 offset:2560
	v_exp_f32_e32 v62, v62
	v_exp_f32_e32 v63, v63
	v_exp_f32_e32 v64, v64
	v_exp_f32_e32 v65, v65
	ds_read_b128 v[140:143], v74 offset:4096
	ds_read_b128 v[236:239], v74 offset:4608
	v_exp_f32_e32 v34, v70
	v_exp_f32_e32 v35, v71
	v_exp_f32_e32 v36, v72
	v_exp_f32_e32 v37, v73
	ds_read_b128 v[240:243], v74 offset:6144
	ds_read_b128 v[244:247], v74 offset:6656
	v_exp_f32_e32 v38, v38
	v_exp_f32_e32 v39, v39
	v_exp_f32_e32 v40, v40
	v_exp_f32_e32 v41, v41
	s_nop 0
	v_exp_f32_e32 v42, v42
	v_exp_f32_e32 v43, v43
	v_exp_f32_e32 v44, v44
	v_exp_f32_e32 v45, v45
	s_nop 0
	v_exp_f32_e32 v46, v46
	v_exp_f32_e32 v47, v47
	v_exp_f32_e32 v48, v48
	v_exp_f32_e32 v49, v49
	s_add_i32 s14, s72, 0x2000
	s_cmpk_lg_i32 s72, 0x4000
	s_cselect_b32 s59, s14, 0
	s_waitcnt vmcnt(2) lgkmcnt(0)
	s_barrier
	v_mfma_f32_32x32x16_bf16 v[66:81], v[66:69], v[124:127], 0
	s_add_i32 s98, s72, s68
	s_mov_b32 s99, m0
	s_mov_b32 m0, s98
	s_nop 0
	global_load_lds_dwordx4 v[214:215], off
	s_add_i32 s98, s59, s69
	s_mov_b32 m0, s98
	s_nop 0
	global_load_lds_dwordx4 v[212:213], off
	s_mov_b32 m0, s99
	v_add_u32_e32 v110, s16, v235
	ds_read_b64_tr_b16 v[198:199], v110 offset:24576
	ds_read_b64_tr_b16 v[200:201], v110 offset:25088
	v_add_f32_e32 v254, v50, v51
	v_add_f32_e32 v254, v52, v254
	v_add_f32_e32 v254, v53, v254
	v_add_f32_e32 v254, v54, v254
	v_add_f32_e32 v86, v55, v254
	s_waitcnt lgkmcnt(9)
	v_cvt_pk_bf16_f32 v50, v50, v51
	v_mov_b64_e32 v[128:129], v[174:175]
	v_mov_b64_e32 v[130:131], v[176:177]
	v_mov_b32_e32 v128, v50
	v_cvt_pk_bf16_f32 v129, v52, v53
	ds_read_b64_tr_b16 v[106:107], v110 offset:28672
	ds_read_b64_tr_b16 v[108:109], v110 offset:29184
	v_add_f32_e32 v50, v56, v86
	v_add_f32_e32 v50, v57, v50
	v_add_f32_e32 v50, v58, v50
	v_add_f32_e32 v50, v59, v50
	v_cvt_pk_bf16_f32 v130, v54, v55
	v_cvt_pk_bf16_f32 v131, v56, v57
	s_waitcnt lgkmcnt(10)
	v_mfma_f32_32x32x16_bf16 v[82:97], v[82:85], v[124:127], 0
	ds_read_b64_tr_b16 v[98:99], v110 offset:25600
	ds_read_b64_tr_b16 v[100:101], v110 offset:26112
	s_waitcnt lgkmcnt(11)
	v_mfma_f32_32x32x16_bf16 v[66:81], v[102:105], v[120:123], v[66:81]
	v_add_f32_e32 v50, v60, v50
	v_add_f32_e32 v50, v61, v50
	v_add_f32_e32 v50, v62, v50
	v_cvt_pk_bf16_f32 v51, v58, v59
	v_mov_b64_e32 v[136:137], v[178:179]
	v_add_f32_e32 v50, v63, v50
	v_mov_b64_e32 v[138:139], v[180:181]
	v_mov_b32_e32 v136, v51
	v_cvt_pk_bf16_f32 v137, v60, v61
	ds_read_b64_tr_b16 v[102:103], v110 offset:29696
	ds_read_b64_tr_b16 v[104:105], v110 offset:30208
	v_add_f32_e32 v50, v64, v50
	v_add_f32_e32 v50, v65, v50
	v_add_f32_e32 v50, v34, v50
	v_add_f32_e32 v50, v35, v50
	v_cvt_pk_bf16_f32 v138, v62, v63
	v_cvt_pk_bf16_f32 v139, v64, v65
	s_waitcnt lgkmcnt(12)
	v_mfma_f32_32x32x16_bf16 v[82:97], v[132:135], v[120:123], v[82:97]
	ds_read_b64_tr_b16 v[144:145], v110 offset:26624
	ds_read_b64_tr_b16 v[146:147], v110 offset:27136
	s_waitcnt lgkmcnt(13)
	v_mfma_f32_32x32x16_bf16 v[66:81], v[140:143], v[116:119], v[66:81]
	v_add_f32_e32 v50, v36, v50
	v_add_f32_e32 v50, v37, v50
	v_add_f32_e32 v50, v38, v50
	v_cvt_pk_bf16_f32 v34, v34, v35
	v_mov_b64_e32 v[132:133], v[182:183]
	v_add_f32_e32 v50, v39, v50
	v_mov_b64_e32 v[134:135], v[184:185]
	v_mov_b32_e32 v132, v34
	v_cvt_pk_bf16_f32 v133, v36, v37
	ds_read_b64_tr_b16 v[34:35], v110 offset:30720
	ds_read_b64_tr_b16 v[36:37], v110 offset:31232
	v_add_f32_e32 v50, v40, v50
	v_add_f32_e32 v50, v41, v50
	v_add_f32_e32 v50, v42, v50
	v_add_f32_e32 v50, v43, v50
	v_cvt_pk_bf16_f32 v134, v38, v39
	v_cvt_pk_bf16_f32 v135, v40, v41
	s_waitcnt lgkmcnt(14)
	v_mfma_f32_32x32x16_bf16 v[82:97], v[236:239], v[116:119], v[82:97]
	ds_read_b64_tr_b16 v[38:39], v110 offset:27648
	ds_read_b64_tr_b16 v[40:41], v110 offset:28160
	s_waitcnt lgkmcnt(14)
	v_mfma_f32_32x32x16_bf16 v[66:81], v[240:243], v[112:115], v[66:81]
	v_add_f32_e32 v50, v44, v50
	v_add_f32_e32 v50, v45, v50
	v_add_f32_e32 v50, v46, v50
	v_cvt_pk_bf16_f32 v42, v42, v43
	v_mov_b64_e32 v[140:141], v[186:187]
	v_add_f32_e32 v50, v47, v50
	v_mov_b64_e32 v[142:143], v[188:189]
	v_mov_b32_e32 v140, v42
	v_cvt_pk_bf16_f32 v141, v44, v45
	ds_read_b64_tr_b16 v[42:43], v110 offset:31744
	ds_read_b64_tr_b16 v[44:45], v110 offset:32256
	v_add_f32_e32 v50, v48, v50
	v_add_f32_e32 v50, v49, v50
	v_add_f32_e32 v64, 0, v50
	v_cvt_pk_bf16_f32 v142, v46, v47
	v_cvt_pk_bf16_f32 v143, v48, v49
	v_mfma_f32_32x32x16_bf16 v[82:97], v[244:247], v[112:115], v[82:97]
	v_mfma_f32_32x32x16_bf16 v[0:15], v[174:177], v[190:193], v[0:15]
	ds_read_b128 v[50:53], v33 offset:384
	ds_read_b128 v[54:57], v33 offset:256
	ds_read_b128 v[58:61], v33 offset:288
	v_add_f32_e32 v32, v32, v172
	v_add_f32_e32 v32, v32, v64
	v_mfma_f32_32x32x16_bf16 v[16:31], v[174:177], v[194:197], v[16:31]
	s_waitcnt lgkmcnt(1)
; #define WAIT_BAR(N) asm volatile("s_waitcnt vmcnt(" #N ") lgkmcnt(0)\n\ts_barrier":::"memory")
;   #define RESC() do{}while(0)
;   #define ROT() do{sl_prev=sl_cur;sl_cur=sl_next;sl_next=(sl_next==(NSLOT-1)*SLOTB)?0:sl_next+SLOTB;}while(0)
; template<int THRL> __device__ __forceinline__ void attn_unit(int b,int h,int qb,int t0,float cqv,float mfix,const float*__restrict__ cf,float cref,unsigned*counter,const bf16*Q,const bf16*__restrict__ K,const bf16*__restrict__ V,bf16*O,const bf16*__restrict__ G,char*shm){
;     ...
;   int t=1;
;     ...
;   for(;t+5<NT;t+=2){
;     STEP(pB0,pB1,pA0,pA1,t,true,true,true);     WAIT_BAR(2); RESC(); ROT();
;     STEP(pA0,pA1,pB0,pB1,t+1,true,true,true);   WAIT_BAR(2); RESC(); ROT();
	v_sub_f32_e32 v46, v206, v54
	v_sub_f32_e32 v47, v206, v55
	v_add_f32_e32 v48, v66, v46
	v_sub_f32_e32 v46, v206, v50
	v_add_f32_e32 v49, v67, v47
	v_sub_f32_e32 v47, v206, v51
	v_sub_f32_e32 v50, v206, v56
	v_mfma_f32_32x32x16_bf16 v[0:15], v[178:181], v[164:167], v[0:15]
	v_sub_f32_e32 v51, v206, v57
	s_waitcnt lgkmcnt(0)
	v_add_f32_e64 v56, v206, -v58
	v_add_f32_e64 v57, v207, -v59
	v_add_f32_e32 v66, v68, v50
	v_add_f32_e32 v67, v69, v51
	v_pk_add_f32 v[68:69], v[70:71], v[56:57]
	v_pk_add_f32 v[56:57], v[206:207], v[60:61] neg_lo:[0,1] neg_hi:[0,1]
	v_sub_f32_e32 v50, v206, v52
	v_mfma_f32_32x32x16_bf16 v[16:31], v[178:181], v[168:171], v[16:31]
	v_sub_f32_e32 v51, v206, v53
	ds_read_b128 v[52:55], v33 offset:416
	v_add_f32_e64 v70, v72, v56
	v_add_f32_e64 v71, v73, v57
	ds_read_b128 v[56:59], v33 offset:320
	ds_read_b128 v[60:63], v33 offset:448
	v_add_f32_e32 v46, v82, v46
	v_add_f32_e32 v47, v83, v47
	v_add_f32_e32 v50, v84, v50
	v_mfma_f32_32x32x16_bf16 v[0:15], v[182:185], v[160:163], v[0:15]
	s_waitcnt lgkmcnt(1)
	v_add_f32_e64 v56, v206, -v56
	v_add_f32_e64 v57, v207, -v57
	v_add_f32_e64 v58, v206, -v58
	v_add_f32_e64 v59, v207, -v59
	v_add_f32_e32 v51, v85, v51
	v_pk_add_f32 v[72:73], v[74:75], v[56:57]
	s_waitcnt lgkmcnt(0)
	v_pk_add_f32 v[56:57], v[206:207], v[60:61] neg_lo:[0,1] neg_hi:[0,1]
	v_pk_add_f32 v[74:75], v[76:77], v[58:59]
	v_pk_add_f32 v[58:59], v[206:207], v[62:63] neg_lo:[0,1] neg_hi:[0,1]
	v_mfma_f32_32x32x16_bf16 v[16:31], v[182:185], v[156:159], v[16:31]
	ds_read_b128 v[60:63], v33 offset:352
	ds_read_b128 v[82:85], v33 offset:480
	v_add_f32_e64 v52, v206, -v52
	v_add_f32_e64 v53, v207, -v53
	v_add_f32_e64 v54, v206, -v54
	v_add_f32_e64 v55, v207, -v55
	v_pk_add_f32 v[52:53], v[86:87], v[52:53]
	s_waitcnt lgkmcnt(1)
	v_pk_add_f32 v[60:61], v[206:207], v[60:61] neg_lo:[0,1] neg_hi:[0,1]
	v_pk_add_f32 v[62:63], v[206:207], v[62:63] neg_lo:[0,1] neg_hi:[0,1]
	v_pk_add_f32 v[76:77], v[78:79], v[60:61]
	v_mfma_f32_32x32x16_bf16 v[0:15], v[186:189], v[152:155], v[0:15]
	s_waitcnt lgkmcnt(0)
	v_add_f32_e64 v60, v206, -v82
	v_add_f32_e64 v61, v207, -v83
	v_add_f32_e64 v78, v80, v62
	v_add_f32_e64 v79, v81, v63
	v_pk_add_f32 v[62:63], v[206:207], v[84:85] neg_lo:[0,1] neg_hi:[0,1]
	v_pk_add_f32 v[54:55], v[88:89], v[54:55]
	v_pk_add_f32 v[56:57], v[90:91], v[56:57]
	v_pk_add_f32 v[58:59], v[92:93], v[58:59]
	v_pk_add_f32 v[60:61], v[94:95], v[60:61]
	v_mfma_f32_32x32x16_bf16 v[16:31], v[186:189], v[148:151], v[16:31]
	v_add_f32_e64 v62, v96, v62
	v_add_f32_e64 v63, v97, v63
	v_mfma_f32_32x32x16_bf16 v[0:15], v[128:131], v[198:201], v[0:15]
	v_exp_f32_e32 v64, v48
	v_exp_f32_e32 v65, v49
	v_exp_f32_e32 v66, v66
	v_exp_f32_e32 v67, v67
	v_mfma_f32_32x32x16_bf16 v[16:31], v[128:131], v[106:109], v[16:31]
	v_exp_f32_e32 v68, v68
	v_exp_f32_e32 v69, v69
	v_exp_f32_e32 v70, v70
	v_exp_f32_e32 v71, v71
	v_add_u32_e32 v80, s59, v233
	ds_read_b128 v[172:175], v80
	ds_read_b128 v[164:167], v80 offset:512
	v_mfma_f32_32x32x16_bf16 v[0:15], v[136:139], v[98:101], v[0:15]
	v_exp_f32_e32 v72, v72
	v_exp_f32_e32 v73, v73
	v_exp_f32_e32 v74, v74
	v_exp_f32_e32 v75, v75
	ds_read_b128 v[168:171], v80 offset:2048
	ds_read_b128 v[160:163], v80 offset:2560
	v_mfma_f32_32x32x16_bf16 v[16:31], v[136:139], v[102:105], v[16:31]
	v_exp_f32_e32 v76, v76
	v_exp_f32_e32 v77, v77
	v_exp_f32_e32 v78, v78
	v_exp_f32_e32 v79, v79
	ds_read_b128 v[156:159], v80 offset:4096
	ds_read_b128 v[152:155], v80 offset:4608
	v_mfma_f32_32x32x16_bf16 v[0:15], v[132:135], v[144:147], v[0:15]
	v_exp_f32_e32 v48, v46
	v_exp_f32_e32 v49, v47
	v_exp_f32_e32 v50, v50
	v_exp_f32_e32 v51, v51
	ds_read_b128 v[148:151], v80 offset:6144
	ds_read_b128 v[144:147], v80 offset:6656
	v_mfma_f32_32x32x16_bf16 v[16:31], v[132:135], v[34:37], v[16:31]
	v_exp_f32_e32 v52, v52
	v_exp_f32_e32 v53, v53
	v_exp_f32_e32 v54, v54
	v_exp_f32_e32 v55, v55
	v_mfma_f32_32x32x16_bf16 v[0:15], v[140:143], v[38:41], v[0:15]
	v_exp_f32_e32 v56, v56
	v_exp_f32_e32 v57, v57
	v_exp_f32_e32 v58, v58
	v_exp_f32_e32 v59, v59
	v_mfma_f32_32x32x16_bf16 v[16:31], v[140:143], v[42:45], v[16:31]
	v_exp_f32_e32 v60, v60
	v_exp_f32_e32 v61, v61
	v_exp_f32_e32 v62, v62
	v_exp_f32_e32 v63, v63
	s_add_i32 s14, s59, 0x2000
	s_cmpk_lg_i32 s59, 0x4000
	s_cselect_b32 s72, s14, 0
	s_add_i32 s19, s19, 2
	v_lshl_add_u64 v[212:213], v[212:213], 0, s[46:47]
	v_lshl_add_u64 v[214:215], v[214:215], 0, s[46:47]
	v_add_u32_e32 v33, 0x200, v33
	s_mov_b32 s17, s54
	v_mov_b32_e32 v176, v130
	v_mov_b32_e32 v177, v131
	v_mov_b32_e32 v180, v138
	v_mov_b32_e32 v181, v139
	v_mov_b32_e32 v184, v134
	v_mov_b32_e32 v185, v135
	v_mov_b32_e32 v188, v142
	v_mov_b32_e32 v189, v143
	s_cmp_ge_i32 s19, s58
	s_waitcnt vmcnt(2) lgkmcnt(0)
	s_barrier
	s_cbranch_scc0 .LBB0_871
	s_add_i32 s18, s18, -3
	s_lshl_b64 s[38:39], s[36:37], 10
	s_add_i32 s14, s18, 1
	s_cmp_ge_i32 s14, s58
	s_cbranch_scc0 .LBB0_883
